# combined: pooling pass rewritten (4-row blocks share window taps) + attention key loop without V/K register copies (V prefetched into working registers, counted waits)
# speedup vs baseline: 1.0036x; 1.0036x over previous
.LBB0_842:
	s_mov_b32 s45, s9
	s_lshl_b64 s[56:57], s[44:45], 9
	s_add_u32 s56, s46, s56
	v_mul_u32_u24_e32 v68, s8, v218
	s_addc_u32 s57, s47, s57
	v_mov_b32_e32 v195, v1
	v_mul_u32_u24_e32 v66, s8, v181
	v_lshl_add_u64 v[70:71], s[56:57], 0, v[194:195]
	v_lshlrev_b32_e32 v0, 1, v68
	v_lshl_add_u64 v[72:73], v[70:71], 0, v[0:1]
	v_lshlrev_b32_e32 v0, 1, v66
	s_add_u32 s48, s48, s52
	v_lshl_add_u64 v[70:71], v[70:71], 0, v[0:1]
	s_addc_u32 s49, s49, 0
	global_load_dwordx4 v[130:133], v[72:73], off offset:1024
	global_load_dwordx4 v[138:141], v[70:71], off offset:1024
	global_load_dwordx4 v[154:157], v[72:73], off
	global_load_dwordx4 v[158:161], v[70:71], off
	s_lshl_b64 s[56:57], s[44:45], 9
	s_add_u32 s56, s56, s48
	s_addc_u32 s57, s57, s49
	v_lshl_add_u64 v[70:71], s[56:57], 0, v[232:233]
	global_load_dwordx4 v[134:137], v[70:71], off offset:384
	global_load_dwordx4 v[142:145], v[70:71], off offset:256
	global_load_dwordx4 v[146:149], v[70:71], off offset:128
	global_load_dwordx4 v[150:153], v[70:71], off
	v_lshl_add_u64 v[196:197], s[46:47], 0, v[194:195]
	v_lshl_add_u64 v[198:199], s[48:49], 0, v[232:233]
	v_subrev_u32_e32 v195, s44, v189
	v_lshlrev_b32_e32 v0, 1, v66
	v_lshlrev_b32_e32 v200, 1, v68
	s_waitcnt vmcnt(0)
.LBB0_843:
	s_waitcnt vmcnt(4)
	v_mfma_f32_32x32x16_bf16 v[82:97], v[150:153], v[98:101], 0
	s_mov_b32 s8, s44
	s_add_i32 s44, s44, 32
	s_cmp_ge_i32 s44, s53
	s_cselect_b64 s[46:47], -1, 0
	s_cmp_lt_i32 s44, s53
	s_cselect_b32 s8, s44, s8
	v_mfma_f32_32x32x16_bf16 v[66:81], v[150:153], v[114:117], 0
	s_lshl_b64 vcc, s[8:9], 9
	v_lshl_add_u64 v[164:165], vcc, 0, v[196:197]
	v_mov_b32_e32 v201, v1
	v_lshl_add_u64 v[162:163], v[164:165], 0, v[0:1]
	v_lshl_add_u64 v[164:165], v[164:165], 0, v[200:201]
	v_mfma_f32_32x32x16_bf16 v[82:97], v[146:149], v[102:105], v[82:97]
	v_lshl_add_u64 v[166:167], vcc, 0, v[198:199]
	s_andn2_b64 vcc, exec, s[42:43]
	v_mfma_f32_32x32x16_bf16 v[66:81], v[146:149], v[118:121], v[66:81]
	global_load_dwordx4 v[150:153], v[166:167], off
	global_load_dwordx4 v[146:149], v[166:167], off offset:128
	v_mfma_f32_32x32x16_bf16 v[82:97], v[142:145], v[106:109], v[82:97]
	v_mfma_f32_32x32x16_bf16 v[66:81], v[142:145], v[122:125], v[66:81]
	global_load_dwordx4 v[142:145], v[166:167], off offset:256
	s_nop 0
	v_mfma_f32_32x32x16_bf16 v[82:97], v[134:137], v[110:113], v[82:97]
	v_mfma_f32_32x32x16_bf16 v[66:81], v[134:137], v[126:129], v[66:81]
	global_load_dwordx4 v[134:137], v[166:167], off offset:384
	s_sub_i32 s101, s44, s100
	s_add_i32 s101, s101, 32
	s_cmp_le_u32 s101, 0xa0
	s_cbranch_scc1 .LBB0_845
	s_cbranch_vccnz .LBB0_845
	v_add_u32_e32 v201, 27, v195
	s_movk_i32 s8, 0xfeff
	v_cmp_gt_u32_e32 vcc, s8, v201
	v_add_u32_e32 v201, 26, v195
	s_nop 5
	v_cndmask_b32_e32 v82, v82, v205, vcc
	v_cmp_lt_u32_e32 vcc, s82, v201
	v_add_u32_e32 v201, 25, v195
	s_nop 0
	v_cndmask_b32_e32 v83, v205, v83, vcc
	v_cmp_lt_u32_e32 vcc, s82, v201
	v_add_u32_e32 v201, 24, v195
	s_nop 0
	v_cndmask_b32_e32 v84, v205, v84, vcc
	v_cmp_lt_u32_e32 vcc, s82, v201
	v_add_u32_e32 v201, 19, v195
	s_nop 0
	v_cndmask_b32_e32 v85, v205, v85, vcc
	v_cmp_lt_u32_e32 vcc, s82, v201
	v_add_u32_e32 v201, 18, v195
	s_nop 0
	v_cndmask_b32_e32 v86, v205, v86, vcc
	v_cmp_lt_u32_e32 vcc, s82, v201
	v_add_u32_e32 v201, 17, v195
	s_nop 0
	v_cndmask_b32_e32 v87, v205, v87, vcc
	v_cmp_lt_u32_e32 vcc, s82, v201
	v_add_u32_e32 v201, 16, v195
	s_nop 0
	v_cndmask_b32_e32 v88, v205, v88, vcc
	v_cmp_lt_u32_e32 vcc, s82, v201
	v_add_u32_e32 v201, 11, v195
	s_nop 0
	v_cndmask_b32_e32 v89, v205, v89, vcc
	v_cmp_lt_u32_e32 vcc, s82, v201
	v_add_u32_e32 v201, 10, v195
	s_nop 0
	v_cndmask_b32_e32 v90, v205, v90, vcc
	v_cmp_lt_u32_e32 vcc, s82, v201
	v_add_u32_e32 v201, 9, v195
	s_nop 0
	v_cndmask_b32_e32 v91, v205, v91, vcc
	v_cmp_lt_u32_e32 vcc, s82, v201
	v_add_u32_e32 v201, 8, v195
	s_nop 0
	v_cndmask_b32_e32 v92, v205, v92, vcc
	v_cmp_lt_u32_e32 vcc, s82, v201
	v_add_u32_e32 v201, 3, v195
	s_nop 0
	v_cndmask_b32_e32 v93, v205, v93, vcc
	v_cmp_lt_u32_e32 vcc, s82, v201
	v_add_u32_e32 v201, 2, v195
	s_nop 0
	v_cndmask_b32_e32 v94, v205, v94, vcc
	v_cmp_lt_u32_e32 vcc, s82, v201
	v_add_u32_e32 v201, 1, v195
	s_nop 0
	v_cndmask_b32_e32 v95, v205, v95, vcc
	v_cmp_lt_u32_e32 vcc, s82, v201
	v_add_u32_e32 v201, 59, v195
	s_nop 0
	v_cndmask_b32_e32 v96, v205, v96, vcc
	v_cmp_lt_u32_e32 vcc, s82, v195
	s_nop 1
	v_cndmask_b32_e32 v97, v205, v97, vcc
	v_cmp_lt_u32_e32 vcc, s82, v201
	v_add_u32_e32 v201, 58, v195
	s_nop 0
	v_cndmask_b32_e32 v66, v205, v66, vcc
	v_cmp_lt_u32_e32 vcc, s82, v201
	v_add_u32_e32 v201, 57, v195
	s_nop 0
	v_cndmask_b32_e32 v67, v205, v67, vcc
	v_cmp_lt_u32_e32 vcc, s82, v201
	v_add_u32_e32 v201, 56, v195
	s_nop 0
	v_cndmask_b32_e32 v68, v205, v68, vcc
	v_cmp_lt_u32_e32 vcc, s82, v201
	v_add_u32_e32 v201, 51, v195
	s_nop 0
	v_cndmask_b32_e32 v69, v205, v69, vcc
	v_cmp_lt_u32_e32 vcc, s82, v201
	v_add_u32_e32 v201, 50, v195
	s_nop 0
	v_cndmask_b32_e32 v70, v205, v70, vcc
	v_cmp_lt_u32_e32 vcc, s82, v201
	v_add_u32_e32 v201, 49, v195
	s_nop 0
	v_cndmask_b32_e32 v71, v205, v71, vcc
	v_cmp_lt_u32_e32 vcc, s82, v201
	v_add_u32_e32 v201, 48, v195
	s_nop 0
	v_cndmask_b32_e32 v72, v205, v72, vcc
	v_cmp_lt_u32_e32 vcc, s82, v201
	v_add_u32_e32 v201, 43, v195
	s_nop 0
	v_cndmask_b32_e32 v73, v205, v73, vcc
	v_cmp_lt_u32_e32 vcc, s82, v201
	v_add_u32_e32 v201, 42, v195
	s_nop 0
	v_cndmask_b32_e32 v74, v205, v74, vcc
	v_cmp_lt_u32_e32 vcc, s82, v201
	v_add_u32_e32 v201, 41, v195
	s_nop 0
	v_cndmask_b32_e32 v75, v205, v75, vcc
	v_cmp_lt_u32_e32 vcc, s82, v201
	v_add_u32_e32 v201, 40, v195
	s_nop 0
	v_cndmask_b32_e32 v76, v205, v76, vcc
	v_cmp_lt_u32_e32 vcc, s82, v201
	v_add_u32_e32 v201, 35, v195
	s_nop 0
	v_cndmask_b32_e32 v77, v205, v77, vcc
	v_cmp_lt_u32_e32 vcc, s82, v201
	v_add_u32_e32 v201, 34, v195
	s_nop 0
	v_cndmask_b32_e32 v78, v205, v78, vcc
	v_cmp_lt_u32_e32 vcc, s82, v201
	v_add_u32_e32 v201, 33, v195
	s_nop 0
	v_cndmask_b32_e32 v79, v205, v79, vcc
	v_cmp_lt_u32_e32 vcc, s82, v201
	v_add_u32_e32 v201, 32, v195
	s_nop 0
	v_cndmask_b32_e32 v80, v205, v80, vcc
	v_cmp_lt_u32_e32 vcc, s82, v201
	s_nop 1
	v_cndmask_b32_e32 v81, v205, v81, vcc

.LBB0_847:
	v_mov_b32_e32 v230, v191
	v_pk_add_f32 v[82:83], v[82:83], v[230:231] op_sel_hi:[1,0] neg_lo:[0,1] neg_hi:[0,1]
	v_pk_add_f32 v[84:85], v[84:85], v[230:231] op_sel_hi:[1,0] neg_lo:[0,1] neg_hi:[0,1]
	v_pk_add_f32 v[86:87], v[86:87], v[230:231] op_sel_hi:[1,0] neg_lo:[0,1] neg_hi:[0,1]
	v_pk_add_f32 v[88:89], v[88:89], v[230:231] op_sel_hi:[1,0] neg_lo:[0,1] neg_hi:[0,1]
	v_exp_f32_e32 v82, v82
	v_exp_f32_e32 v83, v83
	v_exp_f32_e32 v84, v84
	v_exp_f32_e32 v85, v85
	v_exp_f32_e32 v86, v86
	v_exp_f32_e32 v87, v87
	v_exp_f32_e32 v88, v88
	v_exp_f32_e32 v89, v89
	v_cvt_pk_bf16_f32 v222, v82, v83
	v_cvt_pk_bf16_f32 v223, v84, v85
	v_cvt_pk_bf16_f32 v224, v86, v87
	v_cvt_pk_bf16_f32 v225, v88, v89
	v_max_f32_e32 v201, v67, v67
	v_max_f32_e32 v208, v66, v66
	s_waitcnt vmcnt(4)
	v_mfma_f32_32x32x16_bf16 v[50:65], v[158:161], v[222:225], v[50:65]
	v_max_f32_e32 v201, v208, v201
	v_max3_f32 v201, v201, v68, v69
	v_pk_add_f32 v[90:91], v[90:91], v[230:231] op_sel_hi:[1,0] neg_lo:[0,1] neg_hi:[0,1]
	v_pk_add_f32 v[92:93], v[92:93], v[230:231] op_sel_hi:[1,0] neg_lo:[0,1] neg_hi:[0,1]
	v_pk_add_f32 v[94:95], v[94:95], v[230:231] op_sel_hi:[1,0] neg_lo:[0,1] neg_hi:[0,1]
	v_mfma_f32_32x32x16_bf16 v[34:49], v[138:141], v[222:225], v[34:49]
	v_pk_add_f32 v[96:97], v[96:97], v[230:231] op_sel_hi:[1,0] neg_lo:[0,1] neg_hi:[0,1]
	v_max3_f32 v201, v201, v70, v71
	v_exp_f32_e32 v90, v90
	v_exp_f32_e32 v91, v91
	v_exp_f32_e32 v92, v92
	v_exp_f32_e32 v93, v93
	v_exp_f32_e32 v94, v94
	v_exp_f32_e32 v95, v95
	v_exp_f32_e32 v96, v96
	v_exp_f32_e32 v97, v97
	v_max3_f32 v201, v201, v72, v73
	v_max3_f32 v201, v201, v74, v75
	v_max3_f32 v201, v201, v76, v77
	v_max3_f32 v201, v201, v78, v79
	v_cvt_pk_bf16_f32 v226, v90, v91
	v_cvt_pk_bf16_f32 v227, v92, v93
	v_cvt_pk_bf16_f32 v228, v94, v95
	v_cvt_pk_bf16_f32 v229, v96, v97
	v_max3_f32 v201, v201, v80, v81
	v_mov_b32_e32 v208, v201
	v_mfma_f32_32x32x16_bf16 v[50:65], v[154:157], v[226:229], v[50:65]
	s_nop 0
	v_permlane32_swap_b32_e32 v208, v201
	v_max_f32_e32 v201, v201, v208
	v_add_f32_e32 v208, 0x41000000, v221
	v_cmp_gt_f32_e32 vcc, v201, v208
	v_mfma_f32_32x32x16_bf16 v[34:49], v[130:133], v[226:229], v[34:49]
	s_cbranch_vccz .LBB0_849
	v_max_f32_e32 v201, v201, v201
	v_max_f32_e32 v208, v221, v221
	v_max_f32_e32 v201, v208, v201
	v_sub_f32_e32 v208, v221, v201
	v_exp_f32_e32 v222, v208
	v_mov_b32_e32 v221, v201
	v_mul_f32_e32 v193, v193, v222
	v_pk_mul_f32 v[32:33], v[32:33], v[222:223] op_sel_hi:[1,0]
	v_pk_mul_f32 v[30:31], v[30:31], v[222:223] op_sel_hi:[1,0]
	v_pk_mul_f32 v[28:29], v[28:29], v[222:223] op_sel_hi:[1,0]
	v_pk_mul_f32 v[26:27], v[26:27], v[222:223] op_sel_hi:[1,0]
	v_pk_mul_f32 v[24:25], v[24:25], v[222:223] op_sel_hi:[1,0]
	v_pk_mul_f32 v[22:23], v[22:23], v[222:223] op_sel_hi:[1,0]
	v_pk_mul_f32 v[20:21], v[20:21], v[222:223] op_sel_hi:[1,0]
	v_pk_mul_f32 v[18:19], v[18:19], v[222:223] op_sel_hi:[1,0]
	v_pk_mul_f32 v[16:17], v[16:17], v[222:223] op_sel_hi:[1,0]
	v_pk_mul_f32 v[14:15], v[14:15], v[222:223] op_sel_hi:[1,0]
	v_pk_mul_f32 v[12:13], v[12:13], v[222:223] op_sel_hi:[1,0]
	v_pk_mul_f32 v[10:11], v[10:11], v[222:223] op_sel_hi:[1,0]
	v_pk_mul_f32 v[8:9], v[8:9], v[222:223] op_sel_hi:[1,0]
	v_pk_mul_f32 v[6:7], v[6:7], v[222:223] op_sel_hi:[1,0]
	v_pk_mul_f32 v[4:5], v[4:5], v[222:223] op_sel_hi:[1,0]
	v_pk_mul_f32 v[2:3], v[2:3], v[222:223] op_sel_hi:[1,0]
.LBB0_849:
	v_mov_b32_e32 v234, v221
	v_pk_add_f32 v[66:67], v[66:67], v[234:235] op_sel_hi:[1,0] neg_lo:[0,1] neg_hi:[0,1]
	v_exp_f32_e32 v66, v66
	v_exp_f32_e32 v67, v67
	v_pk_add_f32 v[68:69], v[68:69], v[234:235] op_sel_hi:[1,0] neg_lo:[0,1] neg_hi:[0,1]
	v_exp_f32_e32 v68, v68
	v_pk_add_f32 v[70:71], v[70:71], v[234:235] op_sel_hi:[1,0] neg_lo:[0,1] neg_hi:[0,1]
	v_pk_add_f32 v[72:73], v[72:73], v[234:235] op_sel_hi:[1,0] neg_lo:[0,1] neg_hi:[0,1]
	v_exp_f32_e32 v69, v69
	v_exp_f32_e32 v70, v70
	v_exp_f32_e32 v71, v71
	v_exp_f32_e32 v72, v72
	v_exp_f32_e32 v73, v73
	v_pk_add_f32 v[82:83], v[82:83], v[84:85]
	v_pk_add_f32 v[86:87], v[86:87], v[88:89]
	v_pk_add_f32 v[90:91], v[90:91], v[92:93]
	v_pk_add_f32 v[94:95], v[94:95], v[96:97]
	v_pk_add_f32 v[82:83], v[82:83], v[86:87]
	v_pk_add_f32 v[90:91], v[90:91], v[94:95]
	v_pk_add_f32 v[82:83], v[82:83], v[90:91]
	v_add_f32_e32 v82, v82, v83
	v_add_f32_e32 v220, v220, v82
	v_pk_add_f32 v[82:83], v[66:67], v[68:69]
	v_cvt_pk_bf16_f32 v66, v66, v67
	v_cvt_pk_bf16_f32 v67, v68, v69
	v_cvt_pk_bf16_f32 v68, v70, v71
	v_cvt_pk_bf16_f32 v69, v72, v73
	v_pk_add_f32 v[74:75], v[74:75], v[234:235] op_sel_hi:[1,0] neg_lo:[0,1] neg_hi:[0,1]
	v_pk_add_f32 v[76:77], v[76:77], v[234:235] op_sel_hi:[1,0] neg_lo:[0,1] neg_hi:[0,1]
	v_mfma_f32_32x32x16_bf16 v[18:33], v[158:161], v[66:69], v[18:33]
	v_pk_add_f32 v[78:79], v[78:79], v[234:235] op_sel_hi:[1,0] neg_lo:[0,1] neg_hi:[0,1]
	v_pk_add_f32 v[80:81], v[80:81], v[234:235] op_sel_hi:[1,0] neg_lo:[0,1] neg_hi:[0,1]
	v_mfma_f32_32x32x16_bf16 v[2:17], v[138:141], v[66:69], v[2:17]
	v_exp_f32_e32 v74, v74
	v_exp_f32_e32 v75, v75
	v_exp_f32_e32 v76, v76
	v_exp_f32_e32 v77, v77
	v_exp_f32_e32 v78, v78
	v_exp_f32_e32 v79, v79
	v_exp_f32_e32 v80, v80
	v_exp_f32_e32 v81, v81
	v_pk_add_f32 v[84:85], v[70:71], v[72:73]
	v_cvt_pk_bf16_f32 v70, v74, v75
	v_cvt_pk_bf16_f32 v71, v76, v77
	v_cvt_pk_bf16_f32 v72, v78, v79
	v_cvt_pk_bf16_f32 v73, v80, v81
	v_pk_add_f32 v[86:87], v[74:75], v[76:77]
	v_pk_add_f32 v[88:89], v[78:79], v[80:81]
	v_mfma_f32_32x32x16_bf16 v[18:33], v[154:157], v[70:73], v[18:33]
	v_pk_add_f32 v[82:83], v[82:83], v[84:85]
	v_pk_add_f32 v[86:87], v[86:87], v[88:89]
	v_pk_add_f32 v[82:83], v[82:83], v[86:87]
	v_add_f32_e32 v82, v82, v83
	v_add_f32_e32 v193, v193, v82
	v_subrev_u32_e32 v195, 32, v195
	v_mfma_f32_32x32x16_bf16 v[2:17], v[130:133], v[70:73], v[2:17]
	s_and_b64 vcc, exec, s[46:47]
	s_cbranch_vccnz .LBB0_836
	global_load_dwordx4 v[158:161], v[162:163], off
	global_load_dwordx4 v[154:157], v[164:165], off
	global_load_dwordx4 v[138:141], v[162:163], off offset:1024
	global_load_dwordx4 v[130:133], v[164:165], off offset:1024
	s_branch .LBB0_843
